# V^T projection epilogue: lane-transposed coalesced stores (deferred ds_bpermute), on top of the best kernel
# baseline (speedup 1.0000x reference)
; #define PG8_LAS __attribute__((address_space(3)))
; __device__ __forceinline__ unsigned cvt_pk_bf16(float lo, float hi) { unsigned r; asm volatile("v_cvt_pk_bf16_f32 %0, %1, %2" : "=v"(r) : "v"(lo), "v"(hi)); return r; }
;     __device__ __forceinline__ void operator()(const f32x4 (&acc)[2][2][4][2], const Unit& u, int wr, int wc, int fr, int fq) const {
;         asm volatile("" : "+v"(fr), "+v"(fq));
;         const int rl0 = wr * 64 + fr, cl0 = wc * 32 + 8 * fq;
;         f32x4 sv[2][2];
; #pragma unroll
;         for (int bj = 0; bj < 2; ++bj)
; #pragma unroll
;             for (int n = 0; n < 2; ++n) sv[bj][n] = *(const PG8_LAS f32x4*)(rs + cl0 + bj * HALF + 4 * n);
; #pragma unroll
;         for (int ai = 0; ai < 2; ++ai)
; #pragma unroll
;             for (int m = 0; m < 4; ++m) { const int rl = rl0 + ai * HALF + m * 16; bf16_t* rowp = O + (size_t)(u.pm * BM + rl) * ldc + (size_t)u.pn * BM + cl0;
; #pragma unroll
;                 for (int bj = 0; bj < 2; ++bj) { const f32x4 v0 = acc[ai][bj][m][0] * sv[bj][0], v1 = acc[ai][bj][m][1] * sv[bj][1];
;                     u32x4 w; w.x = cvt_pk_bf16(v0[0], v0[1]); w.y = cvt_pk_bf16(v0[2], v0[3]); w.z = cvt_pk_bf16(v1[0], v1[1]); w.w = cvt_pk_bf16(v1[2], v1[3]);
;                     *(u32x4*)(rowp + bj * HALF) = w; } }
;     }
.LBB0_209:
	v_mbcnt_lo_u32_b32 v246, -1, 0
	v_mbcnt_hi_u32_b32 v246, -1, v246
	v_and_b32_e32 v249, 3, v246
	v_lshrrev_b32_e32 v209, 4, v246
	v_sub_u32_e32 v209, v249, v209
	v_lshlrev_b32_e32 v209, 4, v209
	v_and_b32_e32 v208, 15, v246
	v_lshrrev_b32_e32 v246, 2, v246
	v_sub_u32_e32 v208, v246, v208
	v_lshl_add_u32 v208, v208, 17, v209
	v_ashrrev_i32_e32 v209, 31, v208
	v_lshl_add_u32 v246, v249, 4, v246
	v_lshlrev_b32_e32 v246, 2, v246
	v_mov_b32_e32 v156, v160
	v_mov_b32_e32 v130, v161
	s_lshl_b32 s43, s51, 8
	v_lshl_add_u32 v158, v130, 3, s69
	v_lshl_add_u32 v130, v158, 2, 0
	s_add_i32 s43, s43, s68
	v_add_u32_e32 v130, 0x24000, v130
	v_add_u32_e32 v156, s43, v156
	ds_read_b128 v[142:145], v130
	ds_read_b128 v[138:141], v130 offset:16
	ds_read_b128 v[134:137], v130 offset:512
	ds_read_b128 v[130:133], v130 offset:528
	v_ashrrev_i32_e32 v157, 31, v156
	v_lshlrev_b64 v[164:165], 17, v[156:157]
	s_ashr_i32 s51, s50, 31
	v_ashrrev_i32_e32 v159, 31, v158
	v_lshl_add_u64 v[164:165], s[22:23], 0, v[164:165]
	s_lshl_b64 s[50:51], s[50:51], 9
	v_lshl_add_u64 v[164:165], v[164:165], 0, s[50:51]
	v_lshlrev_b64 v[158:159], 1, v[158:159]
	v_lshl_add_u64 v[164:165], v[164:165], 0, v[158:159]
	s_waitcnt lgkmcnt(0)
	v_pk_mul_f32 v[128:129], v[128:129], v[144:145]
	v_pk_mul_f32 v[126:127], v[126:127], v[142:143]
	v_pk_mul_f32 v[166:167], v[124:125], v[140:141]
	v_pk_mul_f32 v[124:125], v[122:123], v[138:139]
	v_cvt_pk_bf16_f32 v122, v126, v127
	v_cvt_pk_bf16_f32 v123, v128, v129
	v_pk_mul_f32 v[118:119], v[118:119], v[134:135]
	v_cvt_pk_bf16_f32 v124, v124, v125
	v_cvt_pk_bf16_f32 v125, v166, v167
	ds_bpermute_b32 v196, v246, v122
	ds_bpermute_b32 v197, v246, v123
	ds_bpermute_b32 v198, v246, v124
	ds_bpermute_b32 v199, v246, v125
	v_lshl_add_u64 v[204:205], v[164:165], 0, v[208:209]
	v_pk_mul_f32 v[120:121], v[120:121], v[136:137]
	v_pk_mul_f32 v[112:113], v[112:113], v[144:145]
	v_pk_mul_f32 v[122:123], v[116:117], v[132:133]
	v_pk_mul_f32 v[116:117], v[114:115], v[130:131]
	v_cvt_pk_bf16_f32 v114, v118, v119
	v_cvt_pk_bf16_f32 v115, v120, v121
	v_pk_mul_f32 v[110:111], v[110:111], v[142:143]
	v_cvt_pk_bf16_f32 v116, v116, v117
	v_cvt_pk_bf16_f32 v117, v122, v123
	ds_bpermute_b32 v200, v246, v114
	ds_bpermute_b32 v201, v246, v115
	ds_bpermute_b32 v202, v246, v116
	ds_bpermute_b32 v203, v246, v117
	v_lshl_add_u64 v[206:207], v[164:165], 0, v[208:209]
	s_waitcnt lgkmcnt(4)
	global_store_dwordx4 v[204:205], v[196:199], off
	v_pk_mul_f32 v[102:103], v[102:103], v[134:135]
	v_pk_mul_f32 v[104:105], v[104:105], v[136:137]
	v_add_u32_e32 v114, 16, v156
	v_ashrrev_i32_e32 v115, 31, v114
	v_lshlrev_b64 v[114:115], 17, v[114:115]
	v_lshl_add_u64 v[114:115], s[22:23], 0, v[114:115]
	v_lshl_add_u64 v[114:115], v[114:115], 0, s[50:51]
	v_lshl_add_u64 v[114:115], v[114:115], 0, v[158:159]
	v_pk_mul_f32 v[116:117], v[108:109], v[140:141]
	v_pk_mul_f32 v[108:109], v[106:107], v[138:139]
	v_cvt_pk_bf16_f32 v106, v110, v111
	v_cvt_pk_bf16_f32 v107, v112, v113
	v_pk_mul_f32 v[96:97], v[96:97], v[144:145]
	v_cvt_pk_bf16_f32 v108, v108, v109
	v_cvt_pk_bf16_f32 v109, v116, v117
	ds_bpermute_b32 v196, v246, v106
	ds_bpermute_b32 v197, v246, v107
	ds_bpermute_b32 v198, v246, v108
	ds_bpermute_b32 v199, v246, v109
	v_lshl_add_u64 v[204:205], v[114:115], 0, v[208:209]
	s_waitcnt lgkmcnt(4)
	global_store_dwordx4 v[206:207], v[200:203], off offset:256
	v_pk_mul_f32 v[94:95], v[94:95], v[142:143]
	v_pk_mul_f32 v[86:87], v[86:87], v[134:135]
	v_pk_mul_f32 v[106:107], v[100:101], v[132:133]
	v_pk_mul_f32 v[100:101], v[98:99], v[130:131]
	v_cvt_pk_bf16_f32 v98, v102, v103
	v_cvt_pk_bf16_f32 v99, v104, v105
	v_pk_mul_f32 v[88:89], v[88:89], v[136:137]
	v_cvt_pk_bf16_f32 v100, v100, v101
	v_cvt_pk_bf16_f32 v101, v106, v107
	ds_bpermute_b32 v200, v246, v98
	ds_bpermute_b32 v201, v246, v99
	ds_bpermute_b32 v202, v246, v100
	ds_bpermute_b32 v203, v246, v101
	v_lshl_add_u64 v[206:207], v[114:115], 0, v[208:209]
	s_waitcnt lgkmcnt(4)
	global_store_dwordx4 v[204:205], v[196:199], off
	v_pk_mul_f32 v[80:81], v[80:81], v[144:145]
	v_pk_mul_f32 v[78:79], v[78:79], v[142:143]
	v_add_u32_e32 v98, 32, v156
	v_ashrrev_i32_e32 v99, 31, v98
	v_lshlrev_b64 v[98:99], 17, v[98:99]
	v_lshl_add_u64 v[98:99], s[22:23], 0, v[98:99]
	v_lshl_add_u64 v[98:99], v[98:99], 0, s[50:51]
	v_lshl_add_u64 v[98:99], v[98:99], 0, v[158:159]
	v_pk_mul_f32 v[100:101], v[92:93], v[140:141]
	v_pk_mul_f32 v[92:93], v[90:91], v[138:139]
	v_cvt_pk_bf16_f32 v90, v94, v95
	v_cvt_pk_bf16_f32 v91, v96, v97
	v_pk_mul_f32 v[70:71], v[70:71], v[134:135]
	v_cvt_pk_bf16_f32 v92, v92, v93
	v_cvt_pk_bf16_f32 v93, v100, v101
	ds_bpermute_b32 v196, v246, v90
	ds_bpermute_b32 v197, v246, v91
	ds_bpermute_b32 v198, v246, v92
	ds_bpermute_b32 v199, v246, v93
	v_lshl_add_u64 v[204:205], v[98:99], 0, v[208:209]
	s_waitcnt lgkmcnt(4)
	global_store_dwordx4 v[206:207], v[200:203], off offset:256
	v_pk_mul_f32 v[72:73], v[72:73], v[136:137]
	v_pk_mul_f32 v[64:65], v[64:65], v[144:145]
	v_pk_mul_f32 v[90:91], v[84:85], v[132:133]
	v_pk_mul_f32 v[84:85], v[82:83], v[130:131]
	v_cvt_pk_bf16_f32 v82, v86, v87
	v_cvt_pk_bf16_f32 v83, v88, v89
	v_pk_mul_f32 v[62:63], v[62:63], v[142:143]
	v_cvt_pk_bf16_f32 v84, v84, v85
	v_cvt_pk_bf16_f32 v85, v90, v91
	ds_bpermute_b32 v200, v246, v82
	ds_bpermute_b32 v201, v246, v83
	ds_bpermute_b32 v202, v246, v84
	ds_bpermute_b32 v203, v246, v85
	v_lshl_add_u64 v[206:207], v[98:99], 0, v[208:209]
	s_waitcnt lgkmcnt(4)
; __device__ __forceinline__ unsigned cvt_pk_bf16(float lo, float hi) { unsigned r; asm volatile("v_cvt_pk_bf16_f32 %0, %1, %2" : "=v"(r) : "v"(lo), "v"(hi)); return r; }
;     __device__ __forceinline__ void operator()(const f32x4 (&acc)[2][2][4][2], const Unit& u, int wr, int wc, int fr, int fq) const {
;     ...
;         for (int ai = 0; ai < 2; ++ai)
; #pragma unroll
;             for (int m = 0; m < 4; ++m) { const int rl = rl0 + ai * HALF + m * 16; bf16_t* rowp = O + (size_t)(u.pm * BM + rl) * ldc + (size_t)u.pn * BM + cl0;
; #pragma unroll
;                 for (int bj = 0; bj < 2; ++bj) { const f32x4 v0 = acc[ai][bj][m][0] * sv[bj][0], v1 = acc[ai][bj][m][1] * sv[bj][1];
;                     u32x4 w; w.x = cvt_pk_bf16(v0[0], v0[1]); w.y = cvt_pk_bf16(v0[2], v0[3]); w.z = cvt_pk_bf16(v1[0], v1[1]); w.w = cvt_pk_bf16(v1[2], v1[3]);
;                     *(u32x4*)(rowp + bj * HALF) = w; } }
	global_store_dwordx4 v[204:205], v[196:199], off
	v_pk_mul_f32 v[54:55], v[54:55], v[134:135]
	v_pk_mul_f32 v[56:57], v[56:57], v[136:137]
	v_add_u32_e32 v82, 48, v156
	v_ashrrev_i32_e32 v83, 31, v82
	v_lshlrev_b64 v[82:83], 17, v[82:83]
	v_lshl_add_u64 v[82:83], s[22:23], 0, v[82:83]
	v_lshl_add_u64 v[82:83], v[82:83], 0, s[50:51]
	v_lshl_add_u64 v[82:83], v[82:83], 0, v[158:159]
	v_pk_mul_f32 v[84:85], v[76:77], v[140:141]
	v_pk_mul_f32 v[76:77], v[74:75], v[138:139]
	v_cvt_pk_bf16_f32 v74, v78, v79
	v_cvt_pk_bf16_f32 v75, v80, v81
	v_pk_mul_f32 v[48:49], v[48:49], v[144:145]
	v_cvt_pk_bf16_f32 v76, v76, v77
	v_cvt_pk_bf16_f32 v77, v84, v85
	ds_bpermute_b32 v196, v246, v74
	ds_bpermute_b32 v197, v246, v75
	ds_bpermute_b32 v198, v246, v76
	ds_bpermute_b32 v199, v246, v77
	v_lshl_add_u64 v[204:205], v[82:83], 0, v[208:209]
	s_waitcnt lgkmcnt(4)
	global_store_dwordx4 v[206:207], v[200:203], off offset:256
	v_pk_mul_f32 v[46:47], v[46:47], v[142:143]
	v_pk_mul_f32 v[38:39], v[38:39], v[134:135]
	v_pk_mul_f32 v[74:75], v[68:69], v[132:133]
	v_pk_mul_f32 v[68:69], v[66:67], v[130:131]
	v_cvt_pk_bf16_f32 v66, v70, v71
	v_cvt_pk_bf16_f32 v67, v72, v73
	v_pk_mul_f32 v[40:41], v[40:41], v[136:137]
	v_cvt_pk_bf16_f32 v68, v68, v69
	v_cvt_pk_bf16_f32 v69, v74, v75
	ds_bpermute_b32 v200, v246, v66
	ds_bpermute_b32 v201, v246, v67
	ds_bpermute_b32 v202, v246, v68
	ds_bpermute_b32 v203, v246, v69
	v_lshl_add_u64 v[206:207], v[82:83], 0, v[208:209]
	s_waitcnt lgkmcnt(4)
	global_store_dwordx4 v[204:205], v[196:199], off
	v_pk_mul_f32 v[32:33], v[32:33], v[144:145]
	v_pk_mul_f32 v[30:31], v[30:31], v[142:143]
	v_add_u32_e32 v66, 0x80, v156
	v_ashrrev_i32_e32 v67, 31, v66
	v_lshlrev_b64 v[66:67], 17, v[66:67]
	v_lshl_add_u64 v[66:67], s[22:23], 0, v[66:67]
	v_lshl_add_u64 v[66:67], v[66:67], 0, s[50:51]
	v_lshl_add_u64 v[66:67], v[66:67], 0, v[158:159]
	v_pk_mul_f32 v[68:69], v[60:61], v[140:141]
	v_pk_mul_f32 v[60:61], v[58:59], v[138:139]
	v_cvt_pk_bf16_f32 v58, v62, v63
	v_cvt_pk_bf16_f32 v59, v64, v65
	v_pk_mul_f32 v[22:23], v[22:23], v[134:135]
	v_cvt_pk_bf16_f32 v60, v60, v61
	v_cvt_pk_bf16_f32 v61, v68, v69
	ds_bpermute_b32 v196, v246, v58
	ds_bpermute_b32 v197, v246, v59
	ds_bpermute_b32 v198, v246, v60
	ds_bpermute_b32 v199, v246, v61
	v_lshl_add_u64 v[204:205], v[66:67], 0, v[208:209]
	s_waitcnt lgkmcnt(4)
	global_store_dwordx4 v[206:207], v[200:203], off offset:256
	v_pk_mul_f32 v[24:25], v[24:25], v[136:137]
	v_pk_mul_f32 v[16:17], v[16:17], v[144:145]
	v_pk_mul_f32 v[58:59], v[52:53], v[132:133]
	v_pk_mul_f32 v[52:53], v[50:51], v[130:131]
	v_cvt_pk_bf16_f32 v50, v54, v55
	v_cvt_pk_bf16_f32 v51, v56, v57
	v_pk_mul_f32 v[14:15], v[14:15], v[142:143]
	v_cvt_pk_bf16_f32 v52, v52, v53
	v_cvt_pk_bf16_f32 v53, v58, v59
	ds_bpermute_b32 v200, v246, v50
	ds_bpermute_b32 v201, v246, v51
	ds_bpermute_b32 v202, v246, v52
	ds_bpermute_b32 v203, v246, v53
	v_lshl_add_u64 v[206:207], v[66:67], 0, v[208:209]
	s_waitcnt lgkmcnt(4)
	global_store_dwordx4 v[204:205], v[196:199], off
	s_and_b64 vcc, exec, s[36:37]
	s_mov_b64 s[36:37], -1
	v_add_u32_e32 v50, 0x90, v156
	v_ashrrev_i32_e32 v51, 31, v50
	v_lshlrev_b64 v[50:51], 17, v[50:51]
	v_lshl_add_u64 v[50:51], s[22:23], 0, v[50:51]
	v_lshl_add_u64 v[50:51], v[50:51], 0, s[50:51]
	v_lshl_add_u64 v[50:51], v[50:51], 0, v[158:159]
	v_pk_mul_f32 v[52:53], v[44:45], v[140:141]
	v_pk_mul_f32 v[44:45], v[42:43], v[138:139]
	v_cvt_pk_bf16_f32 v42, v46, v47
	v_cvt_pk_bf16_f32 v43, v48, v49
	v_pk_mul_f32 v[8:9], v[8:9], v[136:137]
	v_cvt_pk_bf16_f32 v44, v44, v45
	v_cvt_pk_bf16_f32 v45, v52, v53
	ds_bpermute_b32 v196, v246, v42
	ds_bpermute_b32 v197, v246, v43
	ds_bpermute_b32 v198, v246, v44
	ds_bpermute_b32 v199, v246, v45
	v_lshl_add_u64 v[204:205], v[50:51], 0, v[208:209]
	s_waitcnt lgkmcnt(4)
	global_store_dwordx4 v[206:207], v[200:203], off offset:256
	v_pk_mul_f32 v[6:7], v[6:7], v[134:135]
	s_nop 0
	v_pk_mul_f32 v[42:43], v[36:37], v[132:133]
	v_pk_mul_f32 v[36:37], v[34:35], v[130:131]
	v_cvt_pk_bf16_f32 v34, v38, v39
	v_cvt_pk_bf16_f32 v35, v40, v41
	s_nop 0
	v_cvt_pk_bf16_f32 v36, v36, v37
	v_cvt_pk_bf16_f32 v37, v42, v43
	ds_bpermute_b32 v200, v246, v34
	ds_bpermute_b32 v201, v246, v35
	ds_bpermute_b32 v202, v246, v36
	ds_bpermute_b32 v203, v246, v37
	v_lshl_add_u64 v[206:207], v[50:51], 0, v[208:209]
	s_waitcnt lgkmcnt(4)
	global_store_dwordx4 v[204:205], v[196:199], off
	s_nop 1
	v_add_u32_e32 v34, 0xa0, v156
	v_ashrrev_i32_e32 v35, 31, v34
	v_lshlrev_b64 v[34:35], 17, v[34:35]
	v_lshl_add_u64 v[34:35], s[22:23], 0, v[34:35]
	v_lshl_add_u64 v[34:35], v[34:35], 0, s[50:51]
	v_lshl_add_u64 v[34:35], v[34:35], 0, v[158:159]
	v_pk_mul_f32 v[36:37], v[28:29], v[140:141]
	v_pk_mul_f32 v[28:29], v[26:27], v[138:139]
	v_cvt_pk_bf16_f32 v26, v30, v31
	v_cvt_pk_bf16_f32 v27, v32, v33
	s_nop 0
	v_cvt_pk_bf16_f32 v28, v28, v29
	v_cvt_pk_bf16_f32 v29, v36, v37
	ds_bpermute_b32 v196, v246, v26
	ds_bpermute_b32 v197, v246, v27
	ds_bpermute_b32 v198, v246, v28
	ds_bpermute_b32 v199, v246, v29
	v_lshl_add_u64 v[204:205], v[34:35], 0, v[208:209]
	s_waitcnt lgkmcnt(4)
	global_store_dwordx4 v[206:207], v[200:203], off offset:256
	s_nop 1
	v_pk_mul_f32 v[26:27], v[20:21], v[132:133]
	v_pk_mul_f32 v[20:21], v[18:19], v[130:131]
	v_cvt_pk_bf16_f32 v18, v22, v23
	v_cvt_pk_bf16_f32 v19, v24, v25
	s_nop 0
	v_cvt_pk_bf16_f32 v20, v20, v21
	v_cvt_pk_bf16_f32 v21, v26, v27
	ds_bpermute_b32 v200, v246, v18
	ds_bpermute_b32 v201, v246, v19
	ds_bpermute_b32 v202, v246, v20
	ds_bpermute_b32 v203, v246, v21
	v_lshl_add_u64 v[206:207], v[34:35], 0, v[208:209]
	s_waitcnt lgkmcnt(4)
	global_store_dwordx4 v[204:205], v[196:199], off
	s_nop 1
	v_add_u32_e32 v18, 0xb0, v156
	v_ashrrev_i32_e32 v19, 31, v18
	v_lshlrev_b64 v[18:19], 17, v[18:19]
	v_lshl_add_u64 v[18:19], s[22:23], 0, v[18:19]
	v_lshl_add_u64 v[18:19], v[18:19], 0, s[50:51]
	v_lshl_add_u64 v[18:19], v[18:19], 0, v[158:159]
	v_pk_mul_f32 v[20:21], v[12:13], v[140:141]
	v_pk_mul_f32 v[12:13], v[10:11], v[138:139]
	v_cvt_pk_bf16_f32 v10, v14, v15
	v_cvt_pk_bf16_f32 v11, v16, v17
	s_nop 0
	v_cvt_pk_bf16_f32 v12, v12, v13
	v_cvt_pk_bf16_f32 v13, v20, v21
	ds_bpermute_b32 v196, v246, v10
	ds_bpermute_b32 v197, v246, v11
	ds_bpermute_b32 v198, v246, v12
	ds_bpermute_b32 v199, v246, v13
	v_lshl_add_u64 v[204:205], v[18:19], 0, v[208:209]
	s_waitcnt lgkmcnt(4)
	global_store_dwordx4 v[206:207], v[200:203], off offset:256
	s_nop 1
	v_pk_mul_f32 v[10:11], v[4:5], v[132:133]
	v_pk_mul_f32 v[4:5], v[2:3], v[130:131]
	v_cvt_pk_bf16_f32 v2, v6, v7
	v_cvt_pk_bf16_f32 v3, v8, v9
	s_nop 0
	v_cvt_pk_bf16_f32 v4, v4, v5
	v_cvt_pk_bf16_f32 v5, v10, v11
	ds_bpermute_b32 v200, v246, v2
	ds_bpermute_b32 v201, v246, v3
	ds_bpermute_b32 v202, v246, v4
	ds_bpermute_b32 v203, v246, v5
	v_lshl_add_u64 v[206:207], v[18:19], 0, v[208:209]
	s_waitcnt lgkmcnt(4)
	global_store_dwordx4 v[204:205], v[196:199], off
	s_waitcnt lgkmcnt(0)
	global_store_dwordx4 v[206:207], v[200:203], off offset:256
	s_cbranch_vccnz .LBB0_202
; #define PG8_BAR __builtin_amdgcn_s_barrier()
; template <class Epi, class Sched, bool ALIGN_EPI = false, bool SP2 = false>
; __device__ __forceinline__ void gemm_phase(PG8_LAS unsigned char* lds, const Gemm g, const Sched& S, const Epi& E, int tid_in) {
;     ...
;         cur = nxt; cA = nA; cB = nB; ++ui;
;         if constexpr (ALIGN_EPI) { if (wr == 1) PG8_BAR; }
;     }
	s_andn2_b64 vcc, exec, s[38:39]
	s_cbranch_vccnz .LBB0_201
	s_barrier
	s_branch .LBB0_201
